# f32->bf16 row-convert loop prefetches next row into a second register set; item-start store-drain wait dropped in the four plain transpose loops
# speedup vs baseline: 1.0080x; 1.0034x over previous
; #define LAS __attribute__((address_space(3)))
; __device__ __forceinline__ unsigned cvtpk(float lo, float hi) { f32x2 v = {lo, hi}; bf16x2_t b = __builtin_convertvector(v, bf16x2_t); return __builtin_bit_cast(unsigned, b); }
; __device__ __forceinline__ void transpose_item(const float* W, int K, int N, bf16_t* WT, const float* gain, int mode, LAS float* scr, int item, int lane) {
;     ...
;     for (int i = 0; i < 32; ++i) { const int kk = 2 * i + (lane >> 5); float w = __builtin_nontemporal_load(W + (size_t)(k0 + kk) * N + n0 + (lane & 31)); if (gain) w *= gain[k0 + kk]; scr[kk * 33 + (lane & 31)] = w; }
;     int d0 = n0;
;     if (mode == 1) { const int j = n0 < DFF ? n0 : n0 - DFF; d0 = 256 * (j >> 7) + (j & 127) + (n0 < DFF ? 0 : 128); }
;     const int c = lane & 7;
; #pragma unroll
;     for (int j = 0; j < 4; ++j) { const int n = (lane >> 3) + 8 * j; const LAS float* s = scr + (8 * c) * 33 + n;
;         u32x4 o; o.x = cvtpk(s[0 * 33], s[1 * 33]); o.y = cvtpk(s[2 * 33], s[3 * 33]); o.z = cvtpk(s[4 * 33], s[5 * 33]); o.w = cvtpk(s[6 * 33], s[7 * 33]);
;         *(u32x4*)(WT + (size_t)(d0 + n) * K + k0 + 8 * c) = o; }
.LBB0_312:
	v_lshl_add_u64 v[20:21], v[16:17], 0, s[2:3]
	v_lshl_add_u64 v[22:23], v[14:15], 0, s[2:3]
	v_lshl_add_u64 v[24:25], v[12:13], 0, s[2:3]
	v_lshl_add_u64 v[26:27], v[10:11], 0, s[2:3]
	v_lshl_add_u64 v[28:29], v[8:9], 0, s[2:3]
	v_lshl_add_u64 v[30:31], v[6:7], 0, s[2:3]
	v_lshl_add_u64 v[32:33], v[4:5], 0, s[2:3]
	v_lshl_add_u64 v[34:35], v[2:3], 0, s[2:3]
	global_load_dword v100, v[20:21], off nt
	s_nop 0
	global_load_dword v101, v[22:23], off nt
	global_load_dword v102, v[24:25], off nt
	s_nop 0
	global_load_dword v103, v[26:27], off nt
	global_load_dword v104, v[28:29], off nt
	global_load_dword v105, v[30:31], off nt
	global_load_dword v106, v[32:33], off nt
	s_nop 0
	global_load_dword v107, v[34:35], off nt
	s_add_u32 s2, s2, 0x10000
	s_addc_u32 s3, s3, 0
	v_lshl_add_u64 v[20:21], v[16:17], 0, s[2:3]
	v_lshl_add_u64 v[22:23], v[14:15], 0, s[2:3]
	v_lshl_add_u64 v[24:25], v[12:13], 0, s[2:3]
	v_lshl_add_u64 v[26:27], v[10:11], 0, s[2:3]
	v_lshl_add_u64 v[28:29], v[8:9], 0, s[2:3]
	v_lshl_add_u64 v[30:31], v[6:7], 0, s[2:3]
	v_lshl_add_u64 v[32:33], v[4:5], 0, s[2:3]
	v_lshl_add_u64 v[34:35], v[2:3], 0, s[2:3]
	global_load_dword v116, v[20:21], off nt
	s_nop 0
	global_load_dword v117, v[22:23], off nt
	global_load_dword v118, v[24:25], off nt
	s_nop 0
	global_load_dword v119, v[26:27], off nt
	global_load_dword v120, v[28:29], off nt
	global_load_dword v121, v[30:31], off nt
	global_load_dword v122, v[32:33], off nt
	s_nop 0
	global_load_dword v123, v[34:35], off nt
	s_add_u32 s2, s2, 0x10000
	s_addc_u32 s3, s3, 0
	v_lshl_add_u64 v[20:21], v[16:17], 0, s[2:3]
	v_lshl_add_u64 v[22:23], v[14:15], 0, s[2:3]
	v_lshl_add_u64 v[24:25], v[12:13], 0, s[2:3]
	v_lshl_add_u64 v[26:27], v[10:11], 0, s[2:3]
	v_lshl_add_u64 v[28:29], v[8:9], 0, s[2:3]
	v_lshl_add_u64 v[30:31], v[6:7], 0, s[2:3]
	v_lshl_add_u64 v[32:33], v[4:5], 0, s[2:3]
	v_lshl_add_u64 v[34:35], v[2:3], 0, s[2:3]
	global_load_dword v132, v[20:21], off nt
	s_nop 0
	global_load_dword v133, v[22:23], off nt
	global_load_dword v134, v[24:25], off nt
	s_nop 0
	global_load_dword v135, v[26:27], off nt
	global_load_dword v136, v[28:29], off nt
	global_load_dword v137, v[30:31], off nt
	global_load_dword v138, v[32:33], off nt
	s_nop 0
	global_load_dword v139, v[34:35], off nt
	s_add_u32 s2, s2, 0x10000
	s_addc_u32 s3, s3, 0
	v_lshl_add_u64 v[20:21], v[16:17], 0, s[2:3]
	v_lshl_add_u64 v[22:23], v[14:15], 0, s[2:3]
	v_lshl_add_u64 v[24:25], v[12:13], 0, s[2:3]
	v_lshl_add_u64 v[26:27], v[10:11], 0, s[2:3]
	v_lshl_add_u64 v[28:29], v[8:9], 0, s[2:3]
	v_lshl_add_u64 v[30:31], v[6:7], 0, s[2:3]
	v_lshl_add_u64 v[32:33], v[4:5], 0, s[2:3]
	v_lshl_add_u64 v[34:35], v[2:3], 0, s[2:3]
	global_load_dword v148, v[20:21], off nt
	s_nop 0
	global_load_dword v149, v[22:23], off nt
	global_load_dword v150, v[24:25], off nt
	s_nop 0
	global_load_dword v151, v[26:27], off nt
	global_load_dword v152, v[28:29], off nt
	global_load_dword v153, v[30:31], off nt
	global_load_dword v154, v[32:33], off nt
	s_nop 0
	global_load_dword v155, v[34:35], off nt
	s_add_u32 s2, s2, 0x10000
	s_addc_u32 s3, s3, 0
	v_add_u32_e32 v27, 0x400, v19
	s_waitcnt vmcnt(30)
	ds_write2_b32 v19, v100, v101 offset1:66
	s_waitcnt vmcnt(28)
	ds_write2_b32 v19, v102, v103 offset0:132 offset1:198
	s_waitcnt vmcnt(26)
	ds_write2_b32 v27, v104, v105 offset0:8 offset1:74
	s_waitcnt vmcnt(24)
	ds_write2_b32 v27, v106, v107 offset0:140 offset1:206
	v_add_u32_e32 v19, 0x840, v19
	v_add_u32_e32 v27, 0x400, v19
	s_waitcnt vmcnt(22)
	ds_write2_b32 v19, v116, v117 offset1:66
	s_waitcnt vmcnt(20)
	ds_write2_b32 v19, v118, v119 offset0:132 offset1:198
	s_waitcnt vmcnt(18)
	ds_write2_b32 v27, v120, v121 offset0:8 offset1:74
	s_waitcnt vmcnt(16)
	ds_write2_b32 v27, v122, v123 offset0:140 offset1:206
	v_add_u32_e32 v19, 0x840, v19
	v_add_u32_e32 v27, 0x400, v19
	s_waitcnt vmcnt(14)
	ds_write2_b32 v19, v132, v133 offset1:66
	s_waitcnt vmcnt(12)
	ds_write2_b32 v19, v134, v135 offset0:132 offset1:198
	s_waitcnt vmcnt(10)
	ds_write2_b32 v27, v136, v137 offset0:8 offset1:74
	s_waitcnt vmcnt(8)
	ds_write2_b32 v27, v138, v139 offset0:140 offset1:206
	v_add_u32_e32 v19, 0x840, v19
	v_add_u32_e32 v27, 0x400, v19
	s_waitcnt vmcnt(6)
	ds_write2_b32 v19, v148, v149 offset1:66
	s_waitcnt vmcnt(4)
	ds_write2_b32 v19, v150, v151 offset0:132 offset1:198
	s_waitcnt vmcnt(2)
	ds_write2_b32 v27, v152, v153 offset0:8 offset1:74
	s_waitcnt vmcnt(0)
	ds_write2_b32 v27, v154, v155 offset0:140 offset1:206
	v_add_u32_e32 v19, 0x840, v19
	v_lshlrev_b32_e32 v0, 3, v18
	v_ashrrev_i32_e32 v24, 3, v18
	v_and_b32_e32 v0, 56, v0
	s_lshl_b32 s2, s36, 1
	v_mul_u32_u24_e32 v2, 0x84, v0
	v_lshlrev_b32_e32 v3, 2, v24
	v_readlane_b32 s11, v254, 15
	s_add_i32 s2, s2, 0x1ac00
	s_and_b32 s2, s2, 0x1ffc0
	v_add3_u32 v26, s11, v2, v3
	s_lshl_b32 s3, s36, 5
	ds_read2_b32 v[6:7], v26 offset0:33 offset1:41
	ds_read2_b32 v[8:9], v26 offset1:8
	ds_read2_b32 v[10:11], v26 offset0:66 offset1:74
	ds_read2_b32 v[12:13], v26 offset0:99 offset1:107
	ds_read2_b32 v[14:15], v26 offset0:132 offset1:140
	ds_read2_b32 v[16:17], v26 offset0:165 offset1:173
	ds_read2_b32 v[18:19], v26 offset0:198 offset1:206
	ds_read2_b32 v[20:21], v26 offset0:231 offset1:239
	s_and_b32 s10, s3, 0x3e0
	s_lshl_b32 s2, s2, 1
	s_add_u32 s2, s0, s2
	s_addc_u32 s3, s1, 0
	v_lshlrev_b32_e32 v0, 1, v0
	v_lshl_add_u64 v[22:23], s[2:3], 0, v[0:1]
	v_add_u32_e32 v0, s10, v24
	s_movk_i32 s10, 0x1600
	s_waitcnt lgkmcnt(6)
	v_cvt_pk_bf16_f32 v2, v8, v6
	s_waitcnt lgkmcnt(4)
	v_cvt_pk_bf16_f32 v3, v10, v12
	s_waitcnt lgkmcnt(2)
	v_cvt_pk_bf16_f32 v4, v14, v16
	s_waitcnt lgkmcnt(0)
	v_cvt_pk_bf16_f32 v5, v18, v20
	v_mad_i64_i32 v[24:25], s[2:3], v0, s10, v[22:23]
	global_store_dwordx4 v[24:25], v[2:5], off
	v_add_u32_e32 v6, 8, v0
	s_nop 0
	v_cvt_pk_bf16_f32 v2, v9, v7
	v_cvt_pk_bf16_f32 v3, v11, v13
	v_cvt_pk_bf16_f32 v4, v15, v17
	v_cvt_pk_bf16_f32 v5, v19, v21
	ds_read2_b32 v[8:9], v26 offset0:49 offset1:57
	ds_read2_b32 v[10:11], v26 offset0:16 offset1:24
	ds_read2_b32 v[12:13], v26 offset0:82 offset1:90
	ds_read2_b32 v[14:15], v26 offset0:115 offset1:123
	ds_read2_b32 v[16:17], v26 offset0:148 offset1:156
	ds_read2_b32 v[18:19], v26 offset0:181 offset1:189
	ds_read2_b32 v[20:21], v26 offset0:214 offset1:222
	ds_read2_b32 v[24:25], v26 offset0:247 offset1:255
	v_mad_i64_i32 v[6:7], s[2:3], v6, s10, v[22:23]
	global_store_dwordx4 v[6:7], v[2:5], off
	v_add_u32_e32 v6, 16, v0
	v_mad_i64_i32 v[6:7], s[2:3], v6, s10, v[22:23]
	s_waitcnt lgkmcnt(6)
	v_cvt_pk_bf16_f32 v2, v10, v8
	s_waitcnt lgkmcnt(4)
	v_cvt_pk_bf16_f32 v3, v12, v14
	s_waitcnt lgkmcnt(2)
	v_cvt_pk_bf16_f32 v4, v16, v18
	s_waitcnt lgkmcnt(0)
	v_cvt_pk_bf16_f32 v5, v20, v24
	v_add_u32_e32 v0, 24, v0
	global_store_dwordx4 v[6:7], v[2:5], off
	v_mad_i64_i32 v[6:7], s[2:3], v0, s10, v[22:23]
	s_nop 0
	v_cvt_pk_bf16_f32 v2, v11, v9
	v_cvt_pk_bf16_f32 v3, v13, v15
	v_cvt_pk_bf16_f32 v4, v17, v19
	v_cvt_pk_bf16_f32 v5, v21, v25
	global_store_dwordx4 v[6:7], v[2:5], off
	s_mov_b64 s[2:3], 0

; #define LAS __attribute__((address_space(3)))
; __device__ __forceinline__ unsigned cvtpk(float lo, float hi) { f32x2 v = {lo, hi}; bf16x2_t b = __builtin_convertvector(v, bf16x2_t); return __builtin_bit_cast(unsigned, b); }
; __device__ __forceinline__ void transpose_item(const float* W, int K, int N, bf16_t* WT, const float* gain, int mode, LAS float* scr, int item, int lane) {
;     ...
;     for (int i = 0; i < 32; ++i) { const int kk = 2 * i + (lane >> 5); float w = __builtin_nontemporal_load(W + (size_t)(k0 + kk) * N + n0 + (lane & 31)); if (gain) w *= gain[k0 + kk]; scr[kk * 33 + (lane & 31)] = w; }
;     int d0 = n0;
;     if (mode == 1) { const int j = n0 < DFF ? n0 : n0 - DFF; d0 = 256 * (j >> 7) + (j & 127) + (n0 < DFF ? 0 : 128); }
;     const int c = lane & 7;
; #pragma unroll
;     for (int j = 0; j < 4; ++j) { const int n = (lane >> 3) + 8 * j; const LAS float* s = scr + (8 * c) * 33 + n;
;         u32x4 o; o.x = cvtpk(s[0 * 33], s[1 * 33]); o.y = cvtpk(s[2 * 33], s[3 * 33]); o.z = cvtpk(s[4 * 33], s[5 * 33]); o.w = cvtpk(s[6 * 33], s[7 * 33]);
;         *(u32x4*)(WT + (size_t)(d0 + n) * K + k0 + 8 * c) = o; }
.LBB0_316:
	v_lshl_add_u64 v[20:21], v[16:17], 0, s[2:3]
	v_lshl_add_u64 v[22:23], v[14:15], 0, s[2:3]
	v_lshl_add_u64 v[24:25], v[12:13], 0, s[2:3]
	v_lshl_add_u64 v[26:27], v[10:11], 0, s[2:3]
	v_lshl_add_u64 v[28:29], v[8:9], 0, s[2:3]
	v_lshl_add_u64 v[30:31], v[6:7], 0, s[2:3]
	v_lshl_add_u64 v[32:33], v[4:5], 0, s[2:3]
	v_lshl_add_u64 v[34:35], v[2:3], 0, s[2:3]
	global_load_dword v100, v[20:21], off nt
	s_nop 0
	global_load_dword v101, v[22:23], off nt
	global_load_dword v102, v[24:25], off nt
	s_nop 0
	global_load_dword v103, v[26:27], off nt
	global_load_dword v104, v[28:29], off nt
	global_load_dword v105, v[30:31], off nt
	global_load_dword v106, v[32:33], off nt
	s_nop 0
	global_load_dword v107, v[34:35], off nt
	s_add_u32 s2, s2, 0x10000
	s_addc_u32 s3, s3, 0
	v_lshl_add_u64 v[20:21], v[16:17], 0, s[2:3]
	v_lshl_add_u64 v[22:23], v[14:15], 0, s[2:3]
	v_lshl_add_u64 v[24:25], v[12:13], 0, s[2:3]
	v_lshl_add_u64 v[26:27], v[10:11], 0, s[2:3]
	v_lshl_add_u64 v[28:29], v[8:9], 0, s[2:3]
	v_lshl_add_u64 v[30:31], v[6:7], 0, s[2:3]
	v_lshl_add_u64 v[32:33], v[4:5], 0, s[2:3]
	v_lshl_add_u64 v[34:35], v[2:3], 0, s[2:3]
	global_load_dword v116, v[20:21], off nt
	s_nop 0
	global_load_dword v117, v[22:23], off nt
	global_load_dword v118, v[24:25], off nt
	s_nop 0
	global_load_dword v119, v[26:27], off nt
	global_load_dword v120, v[28:29], off nt
	global_load_dword v121, v[30:31], off nt
	global_load_dword v122, v[32:33], off nt
	s_nop 0
	global_load_dword v123, v[34:35], off nt
	s_add_u32 s2, s2, 0x10000
	s_addc_u32 s3, s3, 0
	v_lshl_add_u64 v[20:21], v[16:17], 0, s[2:3]
	v_lshl_add_u64 v[22:23], v[14:15], 0, s[2:3]
	v_lshl_add_u64 v[24:25], v[12:13], 0, s[2:3]
	v_lshl_add_u64 v[26:27], v[10:11], 0, s[2:3]
	v_lshl_add_u64 v[28:29], v[8:9], 0, s[2:3]
	v_lshl_add_u64 v[30:31], v[6:7], 0, s[2:3]
	v_lshl_add_u64 v[32:33], v[4:5], 0, s[2:3]
	v_lshl_add_u64 v[34:35], v[2:3], 0, s[2:3]
	global_load_dword v132, v[20:21], off nt
	s_nop 0
	global_load_dword v133, v[22:23], off nt
	global_load_dword v134, v[24:25], off nt
	s_nop 0
	global_load_dword v135, v[26:27], off nt
	global_load_dword v136, v[28:29], off nt
	global_load_dword v137, v[30:31], off nt
	global_load_dword v138, v[32:33], off nt
	s_nop 0
	global_load_dword v139, v[34:35], off nt
	s_add_u32 s2, s2, 0x10000
	s_addc_u32 s3, s3, 0
	v_lshl_add_u64 v[20:21], v[16:17], 0, s[2:3]
	v_lshl_add_u64 v[22:23], v[14:15], 0, s[2:3]
	v_lshl_add_u64 v[24:25], v[12:13], 0, s[2:3]
	v_lshl_add_u64 v[26:27], v[10:11], 0, s[2:3]
	v_lshl_add_u64 v[28:29], v[8:9], 0, s[2:3]
	v_lshl_add_u64 v[30:31], v[6:7], 0, s[2:3]
	v_lshl_add_u64 v[32:33], v[4:5], 0, s[2:3]
	v_lshl_add_u64 v[34:35], v[2:3], 0, s[2:3]
	global_load_dword v148, v[20:21], off nt
	s_nop 0
	global_load_dword v149, v[22:23], off nt
	global_load_dword v150, v[24:25], off nt
	s_nop 0
	global_load_dword v151, v[26:27], off nt
	global_load_dword v152, v[28:29], off nt
	global_load_dword v153, v[30:31], off nt
	global_load_dword v154, v[32:33], off nt
	s_nop 0
	global_load_dword v155, v[34:35], off nt
	s_add_u32 s2, s2, 0x10000
	s_addc_u32 s3, s3, 0
	v_add_u32_e32 v27, 0x400, v19
	s_waitcnt vmcnt(30)
	ds_write2_b32 v19, v100, v101 offset1:66
	s_waitcnt vmcnt(28)
	ds_write2_b32 v19, v102, v103 offset0:132 offset1:198
	s_waitcnt vmcnt(26)
	ds_write2_b32 v27, v104, v105 offset0:8 offset1:74
	s_waitcnt vmcnt(24)
	ds_write2_b32 v27, v106, v107 offset0:140 offset1:206
	v_add_u32_e32 v19, 0x840, v19
	v_add_u32_e32 v27, 0x400, v19
	s_waitcnt vmcnt(22)
	ds_write2_b32 v19, v116, v117 offset1:66
	s_waitcnt vmcnt(20)
	ds_write2_b32 v19, v118, v119 offset0:132 offset1:198
	s_waitcnt vmcnt(18)
	ds_write2_b32 v27, v120, v121 offset0:8 offset1:74
	s_waitcnt vmcnt(16)
	ds_write2_b32 v27, v122, v123 offset0:140 offset1:206
	v_add_u32_e32 v19, 0x840, v19
	v_add_u32_e32 v27, 0x400, v19
	s_waitcnt vmcnt(14)
	ds_write2_b32 v19, v132, v133 offset1:66
	s_waitcnt vmcnt(12)
	ds_write2_b32 v19, v134, v135 offset0:132 offset1:198
	s_waitcnt vmcnt(10)
	ds_write2_b32 v27, v136, v137 offset0:8 offset1:74
	s_waitcnt vmcnt(8)
	ds_write2_b32 v27, v138, v139 offset0:140 offset1:206
	v_add_u32_e32 v19, 0x840, v19
	v_add_u32_e32 v27, 0x400, v19
	s_waitcnt vmcnt(6)
	ds_write2_b32 v19, v148, v149 offset1:66
	s_waitcnt vmcnt(4)
	ds_write2_b32 v19, v150, v151 offset0:132 offset1:198
	s_waitcnt vmcnt(2)
	ds_write2_b32 v27, v152, v153 offset0:8 offset1:74
	s_waitcnt vmcnt(0)
	ds_write2_b32 v27, v154, v155 offset0:140 offset1:206
	v_add_u32_e32 v19, 0x840, v19
	v_lshlrev_b32_e32 v0, 3, v18
	v_ashrrev_i32_e32 v24, 3, v18
	v_and_b32_e32 v0, 56, v0
	s_lshl_b32 s2, s36, 1
	v_mul_u32_u24_e32 v2, 0x84, v0
	v_lshlrev_b32_e32 v3, 2, v24
	v_readlane_b32 s11, v254, 15
	s_add_i32 s2, s2, 0x1b700
	s_and_b32 s2, s2, 0x1ffc0
	v_add3_u32 v26, s11, v2, v3
	s_lshl_b32 s3, s36, 5
	ds_read2_b32 v[6:7], v26 offset0:33 offset1:41
	ds_read2_b32 v[8:9], v26 offset1:8
	ds_read2_b32 v[10:11], v26 offset0:66 offset1:74
	ds_read2_b32 v[12:13], v26 offset0:99 offset1:107
	ds_read2_b32 v[14:15], v26 offset0:132 offset1:140
	ds_read2_b32 v[16:17], v26 offset0:165 offset1:173
	ds_read2_b32 v[18:19], v26 offset0:198 offset1:206
	ds_read2_b32 v[20:21], v26 offset0:231 offset1:239
	s_and_b32 s10, s3, 0x3e0
	s_lshl_b32 s2, s2, 1
	s_add_u32 s2, s4, s2
	s_addc_u32 s3, s5, 0
	v_lshlrev_b32_e32 v0, 1, v0
	v_lshl_add_u64 v[22:23], s[2:3], 0, v[0:1]
	v_add_u32_e32 v0, s10, v24
	s_movk_i32 s10, 0x1600
	s_waitcnt lgkmcnt(6)
	v_cvt_pk_bf16_f32 v2, v8, v6
	s_waitcnt lgkmcnt(4)
	v_cvt_pk_bf16_f32 v3, v10, v12
	s_waitcnt lgkmcnt(2)
	v_cvt_pk_bf16_f32 v4, v14, v16
	s_waitcnt lgkmcnt(0)
	v_cvt_pk_bf16_f32 v5, v18, v20
	v_mad_i64_i32 v[24:25], s[2:3], v0, s10, v[22:23]
	global_store_dwordx4 v[24:25], v[2:5], off
	v_add_u32_e32 v6, 8, v0
	s_nop 0
	v_cvt_pk_bf16_f32 v2, v9, v7
	v_cvt_pk_bf16_f32 v3, v11, v13
	v_cvt_pk_bf16_f32 v4, v15, v17
	v_cvt_pk_bf16_f32 v5, v19, v21
	ds_read2_b32 v[8:9], v26 offset0:49 offset1:57
	ds_read2_b32 v[10:11], v26 offset0:16 offset1:24
	ds_read2_b32 v[12:13], v26 offset0:82 offset1:90
	ds_read2_b32 v[14:15], v26 offset0:115 offset1:123
	ds_read2_b32 v[16:17], v26 offset0:148 offset1:156
	ds_read2_b32 v[18:19], v26 offset0:181 offset1:189
	ds_read2_b32 v[20:21], v26 offset0:214 offset1:222
	ds_read2_b32 v[24:25], v26 offset0:247 offset1:255
	v_mad_i64_i32 v[6:7], s[2:3], v6, s10, v[22:23]
	global_store_dwordx4 v[6:7], v[2:5], off
	v_add_u32_e32 v6, 16, v0
	v_mad_i64_i32 v[6:7], s[2:3], v6, s10, v[22:23]
	s_waitcnt lgkmcnt(6)
	v_cvt_pk_bf16_f32 v2, v10, v8
	s_waitcnt lgkmcnt(4)
	v_cvt_pk_bf16_f32 v3, v12, v14
	s_waitcnt lgkmcnt(2)
	v_cvt_pk_bf16_f32 v4, v16, v18
	s_waitcnt lgkmcnt(0)
	v_cvt_pk_bf16_f32 v5, v20, v24
	v_add_u32_e32 v0, 24, v0
	global_store_dwordx4 v[6:7], v[2:5], off
	v_mad_i64_i32 v[6:7], s[2:3], v0, s10, v[22:23]
	s_nop 0
	v_cvt_pk_bf16_f32 v2, v11, v9
	v_cvt_pk_bf16_f32 v3, v13, v15
	v_cvt_pk_bf16_f32 v4, v17, v19
	v_cvt_pk_bf16_f32 v5, v21, v25
	global_store_dwordx4 v[6:7], v[2:5], off

; __device__ __forceinline__ void transpose_item(const float* W, int K, int N, bf16_t* WT, const float* gain, int mode, LAS float* scr, int item, int lane) {
;     ...
;     for (int i = 0; i < 32; ++i) { const int kk = 2 * i + (lane >> 5); float w = __builtin_nontemporal_load(W + (size_t)(k0 + kk) * N + n0 + (lane & 31)); if (gain) w *= gain[k0 + kk]; scr[kk * 33 + (lane & 31)] = w; }
.LBB0_347:
	v_lshl_add_u64 v[20:21], v[16:17], 0, s[2:3]
	v_lshl_add_u64 v[22:23], v[14:15], 0, s[2:3]
	v_lshl_add_u64 v[24:25], v[12:13], 0, s[2:3]
	v_lshl_add_u64 v[26:27], v[10:11], 0, s[2:3]
	v_lshl_add_u64 v[28:29], v[8:9], 0, s[2:3]
	v_lshl_add_u64 v[30:31], v[6:7], 0, s[2:3]
	v_lshl_add_u64 v[32:33], v[4:5], 0, s[2:3]
	v_lshl_add_u64 v[34:35], v[2:3], 0, s[2:3]
	global_load_dword v100, v[20:21], off nt
	s_nop 0
	global_load_dword v101, v[22:23], off nt
	global_load_dword v102, v[24:25], off nt
	s_nop 0
	global_load_dword v103, v[26:27], off nt
	global_load_dword v104, v[28:29], off nt
	global_load_dword v105, v[30:31], off nt
	global_load_dword v106, v[32:33], off nt
	s_nop 0
	global_load_dword v107, v[34:35], off nt
	s_add_u32 s2, s2, 0x10000
	s_addc_u32 s3, s3, 0
	v_lshl_add_u64 v[20:21], v[16:17], 0, s[2:3]
	v_lshl_add_u64 v[22:23], v[14:15], 0, s[2:3]
	v_lshl_add_u64 v[24:25], v[12:13], 0, s[2:3]
	v_lshl_add_u64 v[26:27], v[10:11], 0, s[2:3]
	v_lshl_add_u64 v[28:29], v[8:9], 0, s[2:3]
	v_lshl_add_u64 v[30:31], v[6:7], 0, s[2:3]
	v_lshl_add_u64 v[32:33], v[4:5], 0, s[2:3]
	v_lshl_add_u64 v[34:35], v[2:3], 0, s[2:3]
	global_load_dword v116, v[20:21], off nt
	s_nop 0
	global_load_dword v117, v[22:23], off nt
	global_load_dword v118, v[24:25], off nt
	s_nop 0
	global_load_dword v119, v[26:27], off nt
	global_load_dword v120, v[28:29], off nt
	global_load_dword v121, v[30:31], off nt
	global_load_dword v122, v[32:33], off nt
	s_nop 0
	global_load_dword v123, v[34:35], off nt
	s_add_u32 s2, s2, 0x10000
	s_addc_u32 s3, s3, 0
	v_lshl_add_u64 v[20:21], v[16:17], 0, s[2:3]
	v_lshl_add_u64 v[22:23], v[14:15], 0, s[2:3]
	v_lshl_add_u64 v[24:25], v[12:13], 0, s[2:3]
	v_lshl_add_u64 v[26:27], v[10:11], 0, s[2:3]
	v_lshl_add_u64 v[28:29], v[8:9], 0, s[2:3]
	v_lshl_add_u64 v[30:31], v[6:7], 0, s[2:3]
	v_lshl_add_u64 v[32:33], v[4:5], 0, s[2:3]
	v_lshl_add_u64 v[34:35], v[2:3], 0, s[2:3]
	global_load_dword v132, v[20:21], off nt
	s_nop 0
	global_load_dword v133, v[22:23], off nt
	global_load_dword v134, v[24:25], off nt
	s_nop 0
	global_load_dword v135, v[26:27], off nt
	global_load_dword v136, v[28:29], off nt
	global_load_dword v137, v[30:31], off nt
	global_load_dword v138, v[32:33], off nt
	s_nop 0
	global_load_dword v139, v[34:35], off nt
	s_add_u32 s2, s2, 0x10000
	s_addc_u32 s3, s3, 0
	v_lshl_add_u64 v[20:21], v[16:17], 0, s[2:3]
	v_lshl_add_u64 v[22:23], v[14:15], 0, s[2:3]
	v_lshl_add_u64 v[24:25], v[12:13], 0, s[2:3]
	v_lshl_add_u64 v[26:27], v[10:11], 0, s[2:3]
	v_lshl_add_u64 v[28:29], v[8:9], 0, s[2:3]
	v_lshl_add_u64 v[30:31], v[6:7], 0, s[2:3]
	v_lshl_add_u64 v[32:33], v[4:5], 0, s[2:3]
	v_lshl_add_u64 v[34:35], v[2:3], 0, s[2:3]
	global_load_dword v148, v[20:21], off nt
	s_nop 0
	global_load_dword v149, v[22:23], off nt
	global_load_dword v150, v[24:25], off nt
	s_nop 0
	global_load_dword v151, v[26:27], off nt
	global_load_dword v152, v[28:29], off nt
	global_load_dword v153, v[30:31], off nt
	global_load_dword v154, v[32:33], off nt
	s_nop 0
	global_load_dword v155, v[34:35], off nt
	s_add_u32 s2, s2, 0x10000
	s_addc_u32 s3, s3, 0
	v_add_u32_e32 v27, 0x400, v19
	s_waitcnt vmcnt(30)
	ds_write2_b32 v19, v100, v101 offset1:66
	s_waitcnt vmcnt(28)
	ds_write2_b32 v19, v102, v103 offset0:132 offset1:198
	s_waitcnt vmcnt(26)
	ds_write2_b32 v27, v104, v105 offset0:8 offset1:74
	s_waitcnt vmcnt(24)
	ds_write2_b32 v27, v106, v107 offset0:140 offset1:206
	v_add_u32_e32 v19, 0x840, v19
	v_add_u32_e32 v27, 0x400, v19
	s_waitcnt vmcnt(22)
	ds_write2_b32 v19, v116, v117 offset1:66
	s_waitcnt vmcnt(20)
; #define LAS __attribute__((address_space(3)))
; __device__ __forceinline__ unsigned cvtpk(float lo, float hi) { f32x2 v = {lo, hi}; bf16x2_t b = __builtin_convertvector(v, bf16x2_t); return __builtin_bit_cast(unsigned, b); }
; __device__ __forceinline__ void transpose_item(const float* W, int K, int N, bf16_t* WT, const float* gain, int mode, LAS float* scr, int item, int lane) {
;     ...
;     for (int i = 0; i < 32; ++i) { const int kk = 2 * i + (lane >> 5); float w = __builtin_nontemporal_load(W + (size_t)(k0 + kk) * N + n0 + (lane & 31)); if (gain) w *= gain[k0 + kk]; scr[kk * 33 + (lane & 31)] = w; }
;     int d0 = n0;
;     if (mode == 1) { const int j = n0 < DFF ? n0 : n0 - DFF; d0 = 256 * (j >> 7) + (j & 127) + (n0 < DFF ? 0 : 128); }
;     const int c = lane & 7;
; #pragma unroll
;     for (int j = 0; j < 4; ++j) { const int n = (lane >> 3) + 8 * j; const LAS float* s = scr + (8 * c) * 33 + n;
;         u32x4 o; o.x = cvtpk(s[0 * 33], s[1 * 33]); o.y = cvtpk(s[2 * 33], s[3 * 33]); o.z = cvtpk(s[4 * 33], s[5 * 33]); o.w = cvtpk(s[6 * 33], s[7 * 33]);
;         *(u32x4*)(WT + (size_t)(d0 + n) * K + k0 + 8 * c) = o; }
	ds_write2_b32 v19, v118, v119 offset0:132 offset1:198
	s_waitcnt vmcnt(18)
	ds_write2_b32 v27, v120, v121 offset0:8 offset1:74
	s_waitcnt vmcnt(16)
	ds_write2_b32 v27, v122, v123 offset0:140 offset1:206
	v_add_u32_e32 v19, 0x840, v19
	v_add_u32_e32 v27, 0x400, v19
	s_waitcnt vmcnt(14)
	ds_write2_b32 v19, v132, v133 offset1:66
	s_waitcnt vmcnt(12)
	ds_write2_b32 v19, v134, v135 offset0:132 offset1:198
	s_waitcnt vmcnt(10)
	ds_write2_b32 v27, v136, v137 offset0:8 offset1:74
	s_waitcnt vmcnt(8)
	ds_write2_b32 v27, v138, v139 offset0:140 offset1:206
	v_add_u32_e32 v19, 0x840, v19
	v_add_u32_e32 v27, 0x400, v19
	s_waitcnt vmcnt(6)
	ds_write2_b32 v19, v148, v149 offset1:66
	s_waitcnt vmcnt(4)
	ds_write2_b32 v19, v150, v151 offset0:132 offset1:198
	s_waitcnt vmcnt(2)
	ds_write2_b32 v27, v152, v153 offset0:8 offset1:74
	s_waitcnt vmcnt(0)
	ds_write2_b32 v27, v154, v155 offset0:140 offset1:206
	v_add_u32_e32 v19, 0x840, v19
	v_lshlrev_b32_e32 v0, 3, v18
	v_ashrrev_i32_e32 v24, 3, v18
	v_and_b32_e32 v0, 56, v0
	s_lshl_b32 s2, s36, 1
	v_mul_u32_u24_e32 v2, 0x84, v0
	v_lshlrev_b32_e32 v3, 2, v24
	v_readlane_b32 s11, v254, 15
	s_add_i32 s2, s2, 0x1e700
	s_and_b32 s2, s2, 0x1ffc0
	v_add3_u32 v28, s11, v2, v3
	s_lshl_b32 s3, s36, 5
	ds_read2_b32 v[6:7], v28 offset0:33 offset1:41
	ds_read2_b32 v[8:9], v28 offset1:8
	ds_read2_b32 v[10:11], v28 offset0:66 offset1:74
	ds_read2_b32 v[12:13], v28 offset0:99 offset1:107
	ds_read2_b32 v[14:15], v28 offset0:132 offset1:140
	ds_read2_b32 v[16:17], v28 offset0:165 offset1:173
	ds_read2_b32 v[18:19], v28 offset0:198 offset1:206
	ds_read2_b32 v[20:21], v28 offset0:231 offset1:239
	s_and_b32 s10, s3, 0x3e0
	s_lshl_b32 s2, s2, 1
	s_add_u32 s2, s12, s2
	v_add_u32_e32 v24, s10, v24
	s_addc_u32 s3, s13, 0
	v_lshlrev_b32_e32 v0, 1, v0
	v_ashrrev_i32_e32 v25, 31, v24
	v_lshl_add_u64 v[22:23], s[2:3], 0, v[0:1]
	v_lshlrev_b64 v[26:27], 11, v[24:25]
	s_waitcnt lgkmcnt(6)
	v_cvt_pk_bf16_f32 v2, v8, v6
	s_waitcnt lgkmcnt(4)
	v_cvt_pk_bf16_f32 v3, v10, v12
	s_waitcnt lgkmcnt(2)
	v_cvt_pk_bf16_f32 v4, v14, v16
	s_waitcnt lgkmcnt(0)
	v_cvt_pk_bf16_f32 v5, v18, v20
	v_lshl_add_u64 v[26:27], v[22:23], 0, v[26:27]
	v_add_u32_e32 v6, 8, v24
	global_store_dwordx4 v[26:27], v[2:5], off
	s_nop 1
	v_cvt_pk_bf16_f32 v2, v9, v7
	v_ashrrev_i32_e32 v7, 31, v6
	v_cvt_pk_bf16_f32 v3, v11, v13
	v_cvt_pk_bf16_f32 v4, v15, v17
	v_cvt_pk_bf16_f32 v5, v19, v21
	v_lshlrev_b64 v[6:7], 11, v[6:7]
	ds_read2_b32 v[8:9], v28 offset0:49 offset1:57
	ds_read2_b32 v[10:11], v28 offset0:16 offset1:24
	ds_read2_b32 v[12:13], v28 offset0:82 offset1:90
	ds_read2_b32 v[14:15], v28 offset0:115 offset1:123
	ds_read2_b32 v[16:17], v28 offset0:148 offset1:156
	ds_read2_b32 v[18:19], v28 offset0:181 offset1:189
	ds_read2_b32 v[20:21], v28 offset0:214 offset1:222
	ds_read2_b32 v[26:27], v28 offset0:247 offset1:255
	v_lshl_add_u64 v[6:7], v[22:23], 0, v[6:7]
	global_store_dwordx4 v[6:7], v[2:5], off
	v_add_u32_e32 v6, 16, v24
	v_ashrrev_i32_e32 v7, 31, v6
	v_lshlrev_b64 v[6:7], 11, v[6:7]
	s_waitcnt lgkmcnt(6)
	v_cvt_pk_bf16_f32 v2, v10, v8
	s_waitcnt lgkmcnt(4)
	v_cvt_pk_bf16_f32 v3, v12, v14
	s_waitcnt lgkmcnt(2)
	v_cvt_pk_bf16_f32 v4, v16, v18
	s_waitcnt lgkmcnt(0)
	v_cvt_pk_bf16_f32 v5, v20, v26
	v_lshl_add_u64 v[6:7], v[22:23], 0, v[6:7]
	global_store_dwordx4 v[6:7], v[2:5], off
	v_add_u32_e32 v6, 24, v24
	v_ashrrev_i32_e32 v7, 31, v6
	v_lshlrev_b64 v[6:7], 11, v[6:7]
	v_cvt_pk_bf16_f32 v2, v11, v9
	v_cvt_pk_bf16_f32 v3, v13, v15
	v_cvt_pk_bf16_f32 v4, v17, v19
	v_cvt_pk_bf16_f32 v5, v21, v27
	v_lshl_add_u64 v[6:7], v[22:23], 0, v[6:7]
	global_store_dwordx4 v[6:7], v[2:5], off

; __device__ __forceinline__ void transpose_item(const float* W, int K, int N, bf16_t* WT, const float* gain, int mode, LAS float* scr, int item, int lane) {
;     ...
;     for (int i = 0; i < 32; ++i) { const int kk = 2 * i + (lane >> 5); float w = __builtin_nontemporal_load(W + (size_t)(k0 + kk) * N + n0 + (lane & 31)); if (gain) w *= gain[k0 + kk]; scr[kk * 33 + (lane & 31)] = w; }
.LBB0_357:
	v_lshl_add_u64 v[20:21], v[16:17], 0, s[2:3]
	v_lshl_add_u64 v[22:23], v[14:15], 0, s[2:3]
	v_lshl_add_u64 v[24:25], v[12:13], 0, s[2:3]
	v_lshl_add_u64 v[26:27], v[10:11], 0, s[2:3]
	v_lshl_add_u64 v[28:29], v[8:9], 0, s[2:3]
	v_lshl_add_u64 v[30:31], v[6:7], 0, s[2:3]
	v_lshl_add_u64 v[32:33], v[4:5], 0, s[2:3]
	v_lshl_add_u64 v[34:35], v[2:3], 0, s[2:3]
	global_load_dword v100, v[20:21], off nt
	s_nop 0
	global_load_dword v101, v[22:23], off nt
	global_load_dword v102, v[24:25], off nt
	s_nop 0
	global_load_dword v103, v[26:27], off nt
	global_load_dword v104, v[28:29], off nt
	global_load_dword v105, v[30:31], off nt
	global_load_dword v106, v[32:33], off nt
	s_nop 0
	global_load_dword v107, v[34:35], off nt
	s_add_u32 s2, s2, 0x10000
	s_addc_u32 s3, s3, 0
	v_lshl_add_u64 v[20:21], v[16:17], 0, s[2:3]
	v_lshl_add_u64 v[22:23], v[14:15], 0, s[2:3]
	v_lshl_add_u64 v[24:25], v[12:13], 0, s[2:3]
	v_lshl_add_u64 v[26:27], v[10:11], 0, s[2:3]
	v_lshl_add_u64 v[28:29], v[8:9], 0, s[2:3]
	v_lshl_add_u64 v[30:31], v[6:7], 0, s[2:3]
	v_lshl_add_u64 v[32:33], v[4:5], 0, s[2:3]
	v_lshl_add_u64 v[34:35], v[2:3], 0, s[2:3]
	global_load_dword v116, v[20:21], off nt
	s_nop 0
	global_load_dword v117, v[22:23], off nt
	global_load_dword v118, v[24:25], off nt
	s_nop 0
	global_load_dword v119, v[26:27], off nt
	global_load_dword v120, v[28:29], off nt
	global_load_dword v121, v[30:31], off nt
	global_load_dword v122, v[32:33], off nt
	s_nop 0
	global_load_dword v123, v[34:35], off nt
	s_add_u32 s2, s2, 0x10000
	s_addc_u32 s3, s3, 0
	v_lshl_add_u64 v[20:21], v[16:17], 0, s[2:3]
	v_lshl_add_u64 v[22:23], v[14:15], 0, s[2:3]
	v_lshl_add_u64 v[24:25], v[12:13], 0, s[2:3]
	v_lshl_add_u64 v[26:27], v[10:11], 0, s[2:3]
	v_lshl_add_u64 v[28:29], v[8:9], 0, s[2:3]
	v_lshl_add_u64 v[30:31], v[6:7], 0, s[2:3]
	v_lshl_add_u64 v[32:33], v[4:5], 0, s[2:3]
	v_lshl_add_u64 v[34:35], v[2:3], 0, s[2:3]
	global_load_dword v132, v[20:21], off nt
	s_nop 0
	global_load_dword v133, v[22:23], off nt
	global_load_dword v134, v[24:25], off nt
	s_nop 0
	global_load_dword v135, v[26:27], off nt
	global_load_dword v136, v[28:29], off nt
	global_load_dword v137, v[30:31], off nt
	global_load_dword v138, v[32:33], off nt
	s_nop 0
	global_load_dword v139, v[34:35], off nt
	s_add_u32 s2, s2, 0x10000
	s_addc_u32 s3, s3, 0
	v_lshl_add_u64 v[20:21], v[16:17], 0, s[2:3]
	v_lshl_add_u64 v[22:23], v[14:15], 0, s[2:3]
	v_lshl_add_u64 v[24:25], v[12:13], 0, s[2:3]
	v_lshl_add_u64 v[26:27], v[10:11], 0, s[2:3]
	v_lshl_add_u64 v[28:29], v[8:9], 0, s[2:3]
	v_lshl_add_u64 v[30:31], v[6:7], 0, s[2:3]
	v_lshl_add_u64 v[32:33], v[4:5], 0, s[2:3]
	v_lshl_add_u64 v[34:35], v[2:3], 0, s[2:3]
	global_load_dword v148, v[20:21], off nt
	s_nop 0
	global_load_dword v149, v[22:23], off nt
	global_load_dword v150, v[24:25], off nt
	s_nop 0
	global_load_dword v151, v[26:27], off nt
	global_load_dword v152, v[28:29], off nt
	global_load_dword v153, v[30:31], off nt
	global_load_dword v154, v[32:33], off nt
	s_nop 0
	global_load_dword v155, v[34:35], off nt
	s_add_u32 s2, s2, 0x10000
	s_addc_u32 s3, s3, 0
	v_add_u32_e32 v27, 0x400, v19
	s_waitcnt vmcnt(30)
	ds_write2_b32 v19, v100, v101 offset1:66
	s_waitcnt vmcnt(28)
	ds_write2_b32 v19, v102, v103 offset0:132 offset1:198
	s_waitcnt vmcnt(26)
	ds_write2_b32 v27, v104, v105 offset0:8 offset1:74
	s_waitcnt vmcnt(24)
	ds_write2_b32 v27, v106, v107 offset0:140 offset1:206
	v_add_u32_e32 v19, 0x840, v19
	v_add_u32_e32 v27, 0x400, v19
	s_waitcnt vmcnt(22)
	ds_write2_b32 v19, v116, v117 offset1:66
	s_waitcnt vmcnt(20)
; #define LAS __attribute__((address_space(3)))
; __device__ __forceinline__ unsigned cvtpk(float lo, float hi) { f32x2 v = {lo, hi}; bf16x2_t b = __builtin_convertvector(v, bf16x2_t); return __builtin_bit_cast(unsigned, b); }
; __device__ __forceinline__ void transpose_item(const float* W, int K, int N, bf16_t* WT, const float* gain, int mode, LAS float* scr, int item, int lane) {
;     ...
;     for (int i = 0; i < 32; ++i) { const int kk = 2 * i + (lane >> 5); float w = __builtin_nontemporal_load(W + (size_t)(k0 + kk) * N + n0 + (lane & 31)); if (gain) w *= gain[k0 + kk]; scr[kk * 33 + (lane & 31)] = w; }
;     int d0 = n0;
;     if (mode == 1) { const int j = n0 < DFF ? n0 : n0 - DFF; d0 = 256 * (j >> 7) + (j & 127) + (n0 < DFF ? 0 : 128); }
;     const int c = lane & 7;
; #pragma unroll
;     for (int j = 0; j < 4; ++j) { const int n = (lane >> 3) + 8 * j; const LAS float* s = scr + (8 * c) * 33 + n;
;         u32x4 o; o.x = cvtpk(s[0 * 33], s[1 * 33]); o.y = cvtpk(s[2 * 33], s[3 * 33]); o.z = cvtpk(s[4 * 33], s[5 * 33]); o.w = cvtpk(s[6 * 33], s[7 * 33]);
;         *(u32x4*)(WT + (size_t)(d0 + n) * K + k0 + 8 * c) = o; }
	ds_write2_b32 v19, v118, v119 offset0:132 offset1:198
	s_waitcnt vmcnt(18)
	ds_write2_b32 v27, v120, v121 offset0:8 offset1:74
	s_waitcnt vmcnt(16)
	ds_write2_b32 v27, v122, v123 offset0:140 offset1:206
	v_add_u32_e32 v19, 0x840, v19
	v_add_u32_e32 v27, 0x400, v19
	s_waitcnt vmcnt(14)
	ds_write2_b32 v19, v132, v133 offset1:66
	s_waitcnt vmcnt(12)
	ds_write2_b32 v19, v134, v135 offset0:132 offset1:198
	s_waitcnt vmcnt(10)
	ds_write2_b32 v27, v136, v137 offset0:8 offset1:74
	s_waitcnt vmcnt(8)
	ds_write2_b32 v27, v138, v139 offset0:140 offset1:206
	v_add_u32_e32 v19, 0x840, v19
	v_add_u32_e32 v27, 0x400, v19
	s_waitcnt vmcnt(6)
	ds_write2_b32 v19, v148, v149 offset1:66
	s_waitcnt vmcnt(4)
	ds_write2_b32 v19, v150, v151 offset0:132 offset1:198
	s_waitcnt vmcnt(2)
	ds_write2_b32 v27, v152, v153 offset0:8 offset1:74
	s_waitcnt vmcnt(0)
	ds_write2_b32 v27, v154, v155 offset0:140 offset1:206
	v_add_u32_e32 v19, 0x840, v19
	v_lshlrev_b32_e32 v0, 3, v18
	v_ashrrev_i32_e32 v24, 3, v18
	v_and_b32_e32 v0, 56, v0
	s_lshl_b32 s2, s36, 1
	v_mul_u32_u24_e32 v2, 0x84, v0
	v_lshlrev_b32_e32 v3, 2, v24
	v_readlane_b32 s11, v254, 15
	s_add_i32 s2, s2, 0x1f700
	s_and_b32 s2, s2, 0x1ffc0
	v_add3_u32 v28, s11, v2, v3
	s_lshl_b32 s3, s36, 5
	ds_read2_b32 v[6:7], v28 offset0:33 offset1:41
	ds_read2_b32 v[8:9], v28 offset1:8
	ds_read2_b32 v[10:11], v28 offset0:66 offset1:74
	ds_read2_b32 v[12:13], v28 offset0:99 offset1:107
	ds_read2_b32 v[14:15], v28 offset0:132 offset1:140
	ds_read2_b32 v[16:17], v28 offset0:165 offset1:173
	ds_read2_b32 v[18:19], v28 offset0:198 offset1:206
	ds_read2_b32 v[20:21], v28 offset0:231 offset1:239
	s_and_b32 s10, s3, 0x3e0
	s_lshl_b32 s2, s2, 1
	s_add_u32 s2, s22, s2
	v_add_u32_e32 v24, s10, v24
	s_addc_u32 s3, s23, 0
	v_lshlrev_b32_e32 v0, 1, v0
	v_ashrrev_i32_e32 v25, 31, v24
	v_lshl_add_u64 v[22:23], s[2:3], 0, v[0:1]
	v_lshlrev_b64 v[26:27], 11, v[24:25]
	s_waitcnt lgkmcnt(6)
	v_cvt_pk_bf16_f32 v2, v8, v6
	s_waitcnt lgkmcnt(4)
	v_cvt_pk_bf16_f32 v3, v10, v12
	s_waitcnt lgkmcnt(2)
	v_cvt_pk_bf16_f32 v4, v14, v16
	s_waitcnt lgkmcnt(0)
	v_cvt_pk_bf16_f32 v5, v18, v20
	v_lshl_add_u64 v[26:27], v[22:23], 0, v[26:27]
	v_add_u32_e32 v6, 8, v24
	global_store_dwordx4 v[26:27], v[2:5], off
	s_nop 1
	v_cvt_pk_bf16_f32 v2, v9, v7
	v_ashrrev_i32_e32 v7, 31, v6
	v_cvt_pk_bf16_f32 v3, v11, v13
	v_cvt_pk_bf16_f32 v4, v15, v17
	v_cvt_pk_bf16_f32 v5, v19, v21
	v_lshlrev_b64 v[6:7], 11, v[6:7]
	ds_read2_b32 v[8:9], v28 offset0:49 offset1:57
	ds_read2_b32 v[10:11], v28 offset0:16 offset1:24
	ds_read2_b32 v[12:13], v28 offset0:82 offset1:90
	ds_read2_b32 v[14:15], v28 offset0:115 offset1:123
	ds_read2_b32 v[16:17], v28 offset0:148 offset1:156
	ds_read2_b32 v[18:19], v28 offset0:181 offset1:189
	ds_read2_b32 v[20:21], v28 offset0:214 offset1:222
	ds_read2_b32 v[26:27], v28 offset0:247 offset1:255
	v_lshl_add_u64 v[6:7], v[22:23], 0, v[6:7]
	global_store_dwordx4 v[6:7], v[2:5], off
	v_add_u32_e32 v6, 16, v24
	v_ashrrev_i32_e32 v7, 31, v6
	v_lshlrev_b64 v[6:7], 11, v[6:7]
	s_waitcnt lgkmcnt(6)
	v_cvt_pk_bf16_f32 v2, v10, v8
	s_waitcnt lgkmcnt(4)
	v_cvt_pk_bf16_f32 v3, v12, v14
	s_waitcnt lgkmcnt(2)
	v_cvt_pk_bf16_f32 v4, v16, v18
	s_waitcnt lgkmcnt(0)
	v_cvt_pk_bf16_f32 v5, v20, v26
	v_lshl_add_u64 v[6:7], v[22:23], 0, v[6:7]
	global_store_dwordx4 v[6:7], v[2:5], off
	v_add_u32_e32 v6, 24, v24
	v_ashrrev_i32_e32 v7, 31, v6
	v_lshlrev_b64 v[6:7], 11, v[6:7]
	v_cvt_pk_bf16_f32 v2, v11, v9
	v_cvt_pk_bf16_f32 v3, v13, v15
	v_cvt_pk_bf16_f32 v4, v17, v19
	v_cvt_pk_bf16_f32 v5, v21, v27
	v_lshl_add_u64 v[6:7], v[22:23], 0, v[6:7]
	global_store_dwordx4 v[6:7], v[2:5], off

; __device__ __forceinline__ unsigned cvtpk(float lo, float hi) { f32x2 v = {lo, hi}; bf16x2_t b = __builtin_convertvector(v, bf16x2_t); return __builtin_bit_cast(unsigned, b); }
; __global__ void __launch_bounds__(NTHREADS) fwd_megakernel(Params P) {
;     ...
;                 for (int row = gw; row < RC; row += NGW) { const f32x4* xr = (const f32x4*)(xin + (size_t)row * DM) + lane; f32x4 v[4]; float sq = 0.f;
; #pragma unroll
;                     for (int j = 0; j < 4; ++j) { v[j] = __builtin_nontemporal_load(xr + 64 * j); sq += (v[j].x * v[j].x + v[j].y * v[j].y) + (v[j].z * v[j].z + v[j].w * v[j].w); }
;                     sq = wave_sum(sq); u32x2* o8 = (u32x2*)(XB + (size_t)row * DM) + lane;
; #pragma unroll
;                     for (int j = 0; j < 4; ++j) o8[64 * j] = (u32x2){cvtpk(v[j].x, v[j].y), cvtpk(v[j].z, v[j].w)};
;                     if (lane < 5) ssq[(size_t)lane * RC + row] = lane == 0 ? sq : 0.f; }
.LBB0_391:
	v_readlane_b32 s0, v254, 62
	s_cmp_eq_u32 s0, 24
	s_cbranch_scc1 .LBB0_398
	v_readlane_b32 s0, v255, 13
	s_cmp_gt_i32 s0, 0xffff
	v_readlane_b32 s1, v255, 14
	s_cbranch_scc1 .LBB0_397
	v_and_b32_e32 v0, 64, v223
	v_add_u32_e32 v0, 64, v0
	v_xor_b32_e32 v2, 1, v223
	v_cmp_lt_i32_e32 vcc, v2, v0
	v_readlane_b32 s0, v255, 13
	v_readlane_b32 s1, v255, 14
	v_cndmask_b32_e32 v2, v223, v2, vcc
	v_lshlrev_b32_e32 v8, 2, v2
	v_xor_b32_e32 v2, 2, v223
	v_cmp_lt_i32_e32 vcc, v2, v0
	s_mov_b32 s6, s0
	s_ashr_i32 s7, s0, 31
	v_cndmask_b32_e32 v2, v223, v2, vcc
	v_lshlrev_b32_e32 v9, 2, v2
	v_xor_b32_e32 v2, 4, v223
	v_cmp_lt_i32_e32 vcc, v2, v0
	s_lshl_b64 s[0:1], s[6:7], 2
	v_readlane_b32 s2, v255, 20
	v_cndmask_b32_e32 v2, v223, v2, vcc
	v_lshlrev_b32_e32 v10, 2, v2
	v_xor_b32_e32 v2, 8, v223
	v_cmp_lt_i32_e32 vcc, v2, v0
	s_add_u32 s0, s2, s0
	v_readlane_b32 s2, v255, 23
	v_cndmask_b32_e32 v2, v223, v2, vcc
	v_lshlrev_b32_e32 v11, 2, v2
	v_xor_b32_e32 v2, 16, v223
	v_cmp_lt_i32_e32 vcc, v2, v0
	s_addc_u32 s1, s2, s1
	v_readlane_b32 s2, v255, 21
	v_cndmask_b32_e32 v2, v223, v2, vcc
	v_lshlrev_b32_e32 v12, 2, v2
	v_xor_b32_e32 v2, 32, v223
	v_cmp_lt_i32_e32 vcc, v2, v0
	s_add_u32 s0, s0, s2
	s_addc_u32 s1, s1, 0
	v_cndmask_b32_e32 v0, v223, v2, vcc
	v_lshlrev_b32_e32 v13, 2, v0
	v_lshlrev_b32_e32 v0, 18, v232
	s_waitcnt lgkmcnt(0)
	v_lshl_add_u64 v[2:3], s[0:1], 0, v[0:1]
	v_readlane_b32 s0, v255, 11
	v_readlane_b32 s1, v255, 12
	s_mov_b32 s4, s0
	s_ashr_i32 s5, s0, 31
	s_lshl_b64 s[0:1], s[4:5], 2
	s_lshl_b64 s[2:3], s[6:7], 12
	s_add_u32 s2, s14, s2
	v_lshlrev_b32_e32 v0, 4, v232
	s_addc_u32 s3, s15, s3
	v_lshl_add_u64 v[4:5], s[2:3], 0, v[0:1]
	s_mov_b64 s[2:3], 0xc00
	v_lshl_add_u64 v[4:5], v[4:5], 0, s[2:3]
	s_lshl_b64 s[10:11], s[4:5], 12
	s_mov_b32 s12, s6
	s_lshl_b64 s[2:3], s[6:7], 11
	v_readlane_b32 s6, v255, 26
	s_add_u32 s2, s6, s2
	s_addc_u32 s3, 0, s3
	v_readlane_b32 s6, v255, 27
	v_readlane_b32 s7, v255, 28
	s_add_u32 s2, s6, s2
	v_lshlrev_b32_e32 v0, 3, v232
	s_addc_u32 s3, s7, s3
	v_lshl_add_u64 v[6:7], s[2:3], 0, v[0:1]
	s_mov_b64 s[2:3], 0x400
	v_cmp_gt_u32_e32 vcc, 5, v232
	v_cmp_eq_u32_e64 s[40:41], 0, v232
	v_lshl_add_u64 v[6:7], v[6:7], 0, s[2:3]
	s_mov_b32 s6, s4
	s_lshl_b64 s[2:3], s[4:5], 11
	global_load_dwordx4 v[14:17], v[4:5], off offset:-3072 nt
	global_load_dwordx4 v[18:21], v[4:5], off offset:-2048 nt
	global_load_dwordx4 v[22:25], v[4:5], off offset:-1024 nt
	global_load_dwordx4 v[26:29], v[4:5], off nt
	s_waitcnt vmcnt(0)
	s_branch .LBB0_395
.LBB0_394:
	s_or_b64 exec, exec, s[8:9]
	s_add_i32 s4, s12, s6
	v_lshl_add_u64 v[2:3], v[2:3], 0, s[0:1]
	v_lshl_add_u64 v[4:5], v[4:5], 0, s[10:11]
	s_mov_b32 s12, s4
	s_cmp_gt_i32 s4, 0xffff
	v_lshl_add_u64 v[6:7], v[6:7], 0, s[2:3]
	s_cbranch_scc1 .LBB0_397
	s_waitcnt vmcnt(4)
	v_mov_b32_e32 v14, v100
	v_mov_b32_e32 v15, v101
	v_mov_b32_e32 v16, v102
	v_mov_b32_e32 v17, v103
	v_mov_b32_e32 v18, v104
	v_mov_b32_e32 v19, v105
	v_mov_b32_e32 v20, v106
	v_mov_b32_e32 v21, v107
	v_mov_b32_e32 v22, v108
	v_mov_b32_e32 v23, v109
	v_mov_b32_e32 v24, v110
	v_mov_b32_e32 v25, v111
	v_mov_b32_e32 v26, v112
	v_mov_b32_e32 v27, v113
	v_mov_b32_e32 v28, v114
	v_mov_b32_e32 v29, v115
.LBB0_395:
	s_waitcnt lgkmcnt(0)
	s_add_i32 s42, s12, s6
	s_cmp_gt_i32 s42, 0xffff
	s_cselect_b32 s42, 0, s10
	s_cselect_b32 s43, 0, s11
	v_lshl_add_u64 v[116:117], v[4:5], 0, s[42:43]
	global_load_dwordx4 v[100:103], v[116:117], off offset:-3072 nt
	global_load_dwordx4 v[104:107], v[116:117], off offset:-2048 nt
	global_load_dwordx4 v[108:111], v[116:117], off offset:-1024 nt
	global_load_dwordx4 v[112:115], v[116:117], off nt
	v_mul_f32_e32 v0, v15, v15
	v_mul_f32_e32 v30, v17, v17
	v_mul_f32_e32 v31, v19, v19
	v_mul_f32_e32 v32, v21, v21
	v_mul_f32_e32 v33, v23, v23
	v_mul_f32_e32 v34, v25, v25
	v_fmac_f32_e32 v0, v14, v14
	v_fmac_f32_e32 v30, v16, v16
	v_fmac_f32_e32 v31, v18, v18
	v_fmac_f32_e32 v32, v20, v20
	v_mul_f32_e32 v35, v27, v27
	v_mul_f32_e32 v36, v29, v29
	v_fmac_f32_e32 v33, v22, v22
	v_fmac_f32_e32 v34, v24, v24
	v_add_f32_e32 v0, v0, v30
	v_add_f32_e32 v30, v31, v32
	v_fmac_f32_e32 v35, v26, v26
	v_fmac_f32_e32 v36, v28, v28
	v_add_f32_e32 v31, v33, v34
	v_add_f32_e32 v0, v0, v30
	v_add_f32_e32 v32, v35, v36
	v_add_f32_e32 v0, v0, v31
	v_add_f32_e32 v0, v0, v32
	ds_bpermute_b32 v30, v8, v0
	v_cvt_pk_bf16_f32 v14, v14, v15
	v_cvt_pk_bf16_f32 v15, v16, v17
	v_cvt_pk_bf16_f32 v16, v18, v19
	v_cvt_pk_bf16_f32 v17, v20, v21
	s_waitcnt lgkmcnt(0)
	v_add_f32_e32 v0, v0, v30
	ds_bpermute_b32 v30, v9, v0
	global_store_dwordx2 v[6:7], v[14:15], off offset:-1024
	global_store_dwordx2 v[6:7], v[16:17], off offset:-512
	v_cvt_pk_bf16_f32 v18, v22, v23
	v_cvt_pk_bf16_f32 v16, v26, v27
	v_cvt_pk_bf16_f32 v17, v28, v29
	s_waitcnt lgkmcnt(0)
	v_add_f32_e32 v0, v0, v30
	ds_bpermute_b32 v30, v10, v0
	global_store_dwordx2 v[6:7], v[16:17], off offset:512
	s_waitcnt lgkmcnt(0)
	v_add_f32_e32 v0, v0, v30
	ds_bpermute_b32 v30, v11, v0
	s_waitcnt lgkmcnt(0)
	v_add_f32_e32 v0, v0, v30
	ds_bpermute_b32 v19, v12, v0
	s_waitcnt lgkmcnt(0)
	v_add_f32_e32 v0, v0, v19
	ds_bpermute_b32 v14, v13, v0
	v_cvt_pk_bf16_f32 v19, v24, v25
	global_store_dwordx2 v[6:7], v[18:19], off
	s_and_saveexec_b64 s[8:9], vcc
	s_cbranch_execz .LBB0_394
	s_waitcnt lgkmcnt(0)
	v_add_f32_e32 v0, v0, v14
	v_cndmask_b32_e64 v0, 0, v0, s[40:41]
	global_store_dword v[2:3], v0, off
	s_branch .LBB0_394
